# Resid epilogue: non-returning rowsq atomics, no per-atomic vmcnt(0) drain (plus v2 changes)
# speedup vs baseline: 1.0097x; 1.0097x over previous
.LBB0_500:
	s_lshl_b32 s2, s85, 8
	v_mov_b32_e32 v128, v199
	v_mov_b32_e32 v129, v200
	s_add_i32 s2, s2, s65
	s_nop 0
	v_add_u32_e32 v192, s2, v129
	s_lshl_b32 s2, s84, 8
	s_or_b32 s2, s2, s79
	v_lshl_add_u32 v180, v128, 3, s2
	v_ashrrev_i32_e32 v181, 31, v180
	v_lshlrev_b64 v[208:209], 1, v[180:181]
	v_ashrrev_i32_e32 v193, 31, v192
	v_lshl_add_u64 v[182:183], s[30:31], 0, v[208:209]
	v_lshlrev_b64 v[184:185], 11, v[192:193]
	v_cmp_eq_u32_e32 vcc, 0, v128
	v_lshl_add_u64 v[128:129], v[182:183], 0, v[184:185]
	global_load_dwordx4 v[204:207], v[128:129], off
	global_load_dwordx4 v[152:155], v[128:129], off offset:256
	s_mov_b64 s[2:3], 0x8000
	v_lshl_add_u64 v[190:191], v[184:185], 0, s[2:3]
	s_mov_b64 s[2:3], 0x10000
	v_lshl_add_u64 v[128:129], v[182:183], 0, v[190:191]
	v_lshl_add_u64 v[188:189], v[184:185], 0, s[2:3]
	s_mov_b64 s[2:3], 0x18000
	global_load_dwordx4 v[148:151], v[128:129], off
	global_load_dwordx4 v[144:147], v[128:129], off offset:256
	v_lshl_add_u64 v[128:129], v[182:183], 0, v[188:189]
	v_lshl_add_u64 v[186:187], v[184:185], 0, s[2:3]
	global_load_dwordx4 v[140:143], v[128:129], off
	global_load_dwordx4 v[136:139], v[128:129], off offset:256
	v_lshl_add_u64 v[128:129], v[182:183], 0, v[186:187]
	global_load_dwordx4 v[132:135], v[128:129], off
	s_nop 0
	global_load_dwordx4 v[128:131], v[128:129], off offset:256
	s_waitcnt vmcnt(0)
	v_lshlrev_b32_e32 v210, 16, v204
	v_and_b32_e32 v211, 0xffff0000, v204
	v_lshlrev_b32_e32 v204, 16, v205
	v_and_b32_e32 v205, 0xffff0000, v205
	v_pk_fma_f32 v[212:213], v[174:175], v[126:127], v[204:205]
	v_lshlrev_b32_e32 v204, 16, v206
	v_and_b32_e32 v205, 0xffff0000, v206
	v_pk_fma_f32 v[210:211], v[174:175], v[124:125], v[210:211]
	v_pk_fma_f32 v[214:215], v[174:175], v[120:121], v[204:205]
	v_lshlrev_b32_e32 v204, 16, v207
	v_and_b32_e32 v205, 0xffff0000, v207
	v_pk_mul_f32 v[124:125], v[210:211], v[210:211]
	v_pk_fma_f32 v[216:217], v[174:175], v[122:123], v[204:205]
	v_cvt_pk_bf16_f32 v204, v210, v211
	v_lshl_add_u64 v[210:211], s[30:31], 0, v[184:185]
	v_pk_mul_f32 v[126:127], v[212:213], v[212:213]
	v_pk_mul_f32 v[122:123], v[216:217], v[216:217]
	v_cvt_pk_bf16_f32 v205, v212, v213
	v_cvt_pk_bf16_f32 v206, v214, v215
	v_cvt_pk_bf16_f32 v207, v216, v217
	v_lshl_add_u64 v[208:209], v[210:211], 0, v[208:209]
	v_pk_mul_f32 v[120:121], v[214:215], v[214:215]
	global_store_dwordx4 v[208:209], v[204:207], off
	v_add_f32_e32 v122, v123, v122
	v_add_f32_e32 v123, v127, v126
	v_lshlrev_b32_e32 v204, 16, v152
	v_and_b32_e32 v205, 0xffff0000, v152
	v_add_f32_e32 v124, v125, v124
	v_pk_fma_f32 v[116:117], v[174:175], v[116:117], v[204:205]
	v_lshlrev_b32_e32 v152, 16, v153
	v_and_b32_e32 v153, 0xffff0000, v153
	v_add_f32_e32 v123, v124, v123
	v_add_f32_e32 v120, v121, v120
	v_pk_mul_f32 v[204:205], v[116:117], v[116:117]
	v_pk_fma_f32 v[118:119], v[174:175], v[118:119], v[152:153]
	v_lshlrev_b32_e32 v206, 16, v154
	v_and_b32_e32 v207, 0xffff0000, v154
	v_add_f32_e32 v120, v120, v123
	v_pk_mul_f32 v[152:153], v[118:119], v[118:119]
	v_pk_fma_f32 v[206:207], v[174:175], v[112:113], v[206:207]
	v_lshlrev_b32_e32 v154, 16, v155
	v_and_b32_e32 v155, 0xffff0000, v155
	v_add_f32_e32 v120, v122, v120
	v_add_f32_e32 v121, v205, v204
	v_pk_mul_f32 v[112:113], v[206:207], v[206:207]
	v_pk_fma_f32 v[154:155], v[174:175], v[114:115], v[154:155]
	v_add_f32_e32 v120, v121, v120
	v_add_f32_e32 v121, v153, v152
	v_pk_mul_f32 v[114:115], v[154:155], v[154:155]
	v_add_f32_e32 v120, v121, v120
	v_add_f32_e32 v112, v113, v112
	v_add_f32_e32 v112, v112, v120
	v_add_f32_e32 v113, v115, v114
	v_add_f32_e32 v120, v113, v112
	v_cvt_pk_bf16_f32 v112, v116, v117
	v_cvt_pk_bf16_f32 v113, v118, v119
	v_cvt_pk_bf16_f32 v114, v206, v207
	v_cvt_pk_bf16_f32 v115, v154, v155
	global_store_dwordx4 v[208:209], v[112:115], off offset:256
	ds_bpermute_b32 v112, v157, v120
	s_waitcnt lgkmcnt(0)
	v_add_f32_e32 v116, v120, v112
	ds_bpermute_b32 v117, v194, v116
	v_mov_b64_e32 v[114:115], 0
	v_lshl_add_u64 v[112:113], v[192:193], 3, s[6:7]
	s_and_saveexec_b64 s[34:35], vcc
	s_cbranch_execz .LBB0_502
	s_waitcnt lgkmcnt(0)
	v_add_f32_e32 v114, v116, v117
	v_mul_f32_e32 v114, 0x49800000, v114
	v_trunc_f32_e32 v114, v114
	v_mul_f32_e64 v115, |v114|, s70
	v_floor_f32_e32 v115, v115
	v_fma_f32 v116, v115, s71, |v114|
	v_cvt_u32_f32_e32 v116, v116
	v_cvt_u32_f32_e32 v115, v115
	v_ashrrev_i32_e32 v117, 31, v114
	v_xor_b32_e32 v114, v116, v117
	v_xor_b32_e32 v115, v115, v117
	v_sub_co_u32_e64 v114, s[2:3], v114, v117
	s_nop 1
	v_subb_co_u32_e64 v115, s[2:3], v115, v117, s[2:3]
	global_atomic_add_x2 v[112:113], v[114:115], off
.LBB0_502:
	s_or_b64 exec, exec, s[34:35]
	v_lshlrev_b32_e32 v116, 16, v148
	s_waitcnt lgkmcnt(0)
	v_and_b32_e32 v117, 0xffff0000, v148
	v_lshlrev_b32_e32 v118, 16, v149
	v_and_b32_e32 v119, 0xffff0000, v149
	v_pk_fma_f32 v[108:109], v[174:175], v[108:109], v[116:117]
	v_pk_fma_f32 v[110:111], v[174:175], v[110:111], v[118:119]
	v_lshlrev_b32_e32 v120, 16, v150
	v_and_b32_e32 v121, 0xffff0000, v150
	v_pk_mul_f32 v[116:117], v[108:109], v[108:109]
	v_pk_mul_f32 v[118:119], v[110:111], v[110:111]
	v_pk_fma_f32 v[120:121], v[174:175], v[104:105], v[120:121]
	v_lshlrev_b32_e32 v104, 16, v151
	v_and_b32_e32 v105, 0xffff0000, v151
	v_pk_mul_f32 v[122:123], v[120:121], v[120:121]
	v_pk_fma_f32 v[124:125], v[174:175], v[106:107], v[104:105]
	v_cvt_pk_bf16_f32 v104, v108, v109
	v_lshlrev_b32_e32 v108, 16, v144
	v_and_b32_e32 v109, 0xffff0000, v144
	v_add_f32_e32 v118, v119, v118
	v_add_f32_e32 v116, v117, v116
	v_pk_mul_f32 v[126:127], v[124:125], v[124:125]
	v_cvt_pk_bf16_f32 v105, v110, v111
	v_pk_fma_f32 v[100:101], v[174:175], v[100:101], v[108:109]
	v_lshlrev_b32_e32 v110, 16, v145
	v_and_b32_e32 v111, 0xffff0000, v145
	v_add_f32_e32 v116, v116, v118
	v_add_f32_e32 v117, v123, v122
	v_cvt_pk_bf16_f32 v106, v120, v121
	v_pk_mul_f32 v[108:109], v[100:101], v[100:101]
	v_pk_fma_f32 v[102:103], v[174:175], v[102:103], v[110:111]
	v_lshlrev_b32_e32 v120, 16, v146
	v_and_b32_e32 v121, 0xffff0000, v146
	v_add_f32_e32 v126, v127, v126
	v_add_f32_e32 v116, v117, v116
	v_cvt_pk_bf16_f32 v107, v124, v125
	v_pk_mul_f32 v[110:111], v[102:103], v[102:103]
	v_pk_fma_f32 v[120:121], v[174:175], v[96:97], v[120:121]
	v_lshlrev_b32_e32 v124, 16, v147
	v_and_b32_e32 v125, 0xffff0000, v147
	v_add_f32_e32 v116, v126, v116
	v_add_f32_e32 v108, v109, v108
	v_pk_mul_f32 v[96:97], v[120:121], v[120:121]
	v_pk_fma_f32 v[124:125], v[174:175], v[98:99], v[124:125]
	v_add_f32_e32 v108, v108, v116
	v_add_f32_e32 v109, v111, v110
	v_pk_mul_f32 v[98:99], v[124:125], v[124:125]
	v_add_f32_e32 v108, v109, v108
	v_add_f32_e32 v96, v97, v96
	v_add_f32_e32 v96, v96, v108
	v_add_f32_e32 v97, v99, v98
	v_add_f32_e32 v99, v97, v96
	ds_bpermute_b32 v110, v157, v99
	v_lshl_add_u64 v[96:97], s[30:31], 0, v[190:191]
	v_lshl_add_u64 v[108:109], v[180:181], 1, v[96:97]
	v_cvt_pk_bf16_f32 v98, v100, v101
	v_cvt_pk_bf16_f32 v100, v120, v121
	s_waitcnt lgkmcnt(0)
	v_add_f32_e32 v96, v99, v110
	ds_bpermute_b32 v97, v194, v96
	v_cvt_pk_bf16_f32 v99, v102, v103
	v_cvt_pk_bf16_f32 v101, v124, v125
	global_store_dwordx4 v[108:109], v[104:107], off
	global_store_dwordx4 v[108:109], v[98:101], off offset:256
	s_and_saveexec_b64 s[34:35], vcc
	s_cbranch_execz .LBB0_504
	s_waitcnt lgkmcnt(0)
	v_add_f32_e32 v96, v96, v97
	v_mul_f32_e32 v96, 0x49800000, v96
	v_trunc_f32_e32 v96, v96
	v_mul_f32_e64 v97, |v96|, s70
	v_floor_f32_e32 v97, v97
	v_fma_f32 v98, v97, s71, |v96|
	v_cvt_u32_f32_e32 v98, v98
	v_cvt_u32_f32_e32 v97, v97
	v_ashrrev_i32_e32 v99, 31, v96
	v_xor_b32_e32 v96, v98, v99
	v_xor_b32_e32 v97, v97, v99
	v_sub_co_u32_e64 v96, s[2:3], v96, v99
	s_nop 1
	v_subb_co_u32_e64 v97, s[2:3], v97, v99, s[2:3]
	global_atomic_add_x2 v[112:113], v[96:97], off offset:128
.LBB0_504:
	s_or_b64 exec, exec, s[34:35]
	v_lshlrev_b32_e32 v96, 16, v140
	s_waitcnt lgkmcnt(0)
	v_and_b32_e32 v97, 0xffff0000, v140
	v_lshlrev_b32_e32 v98, 16, v141
	v_and_b32_e32 v99, 0xffff0000, v141
	v_pk_fma_f32 v[92:93], v[174:175], v[92:93], v[96:97]
	v_pk_fma_f32 v[94:95], v[174:175], v[94:95], v[98:99]
	v_lshlrev_b32_e32 v100, 16, v142
	v_and_b32_e32 v101, 0xffff0000, v142
	v_pk_mul_f32 v[96:97], v[92:93], v[92:93]
	v_pk_mul_f32 v[98:99], v[94:95], v[94:95]
	v_pk_fma_f32 v[100:101], v[174:175], v[88:89], v[100:101]
	v_lshlrev_b32_e32 v88, 16, v143
	v_and_b32_e32 v89, 0xffff0000, v143
	v_pk_mul_f32 v[102:103], v[100:101], v[100:101]
	v_pk_fma_f32 v[104:105], v[174:175], v[90:91], v[88:89]
	v_cvt_pk_bf16_f32 v88, v92, v93
	v_lshlrev_b32_e32 v92, 16, v136
	v_and_b32_e32 v93, 0xffff0000, v136
	v_add_f32_e32 v98, v99, v98
	v_add_f32_e32 v96, v97, v96
	v_pk_mul_f32 v[106:107], v[104:105], v[104:105]
	v_cvt_pk_bf16_f32 v89, v94, v95
	v_pk_fma_f32 v[84:85], v[174:175], v[84:85], v[92:93]
	v_lshlrev_b32_e32 v94, 16, v137
	v_and_b32_e32 v95, 0xffff0000, v137
	v_add_f32_e32 v96, v96, v98
	v_add_f32_e32 v97, v103, v102
	v_cvt_pk_bf16_f32 v90, v100, v101
	v_pk_mul_f32 v[92:93], v[84:85], v[84:85]
	v_pk_fma_f32 v[86:87], v[174:175], v[86:87], v[94:95]
	v_lshlrev_b32_e32 v100, 16, v138
	v_and_b32_e32 v101, 0xffff0000, v138
	v_add_f32_e32 v106, v107, v106
	v_add_f32_e32 v96, v97, v96
	v_cvt_pk_bf16_f32 v91, v104, v105
	v_pk_mul_f32 v[94:95], v[86:87], v[86:87]
	v_pk_fma_f32 v[100:101], v[174:175], v[80:81], v[100:101]
	v_lshlrev_b32_e32 v104, 16, v139
	v_and_b32_e32 v105, 0xffff0000, v139
	v_add_f32_e32 v96, v106, v96
	v_add_f32_e32 v92, v93, v92
	v_pk_mul_f32 v[80:81], v[100:101], v[100:101]
	v_pk_fma_f32 v[104:105], v[174:175], v[82:83], v[104:105]
	v_add_f32_e32 v92, v92, v96
	v_add_f32_e32 v93, v95, v94
	v_pk_mul_f32 v[82:83], v[104:105], v[104:105]
	v_add_f32_e32 v92, v93, v92
	v_add_f32_e32 v80, v81, v80
	v_add_f32_e32 v80, v80, v92
	v_add_f32_e32 v81, v83, v82
	v_add_f32_e32 v83, v81, v80
	ds_bpermute_b32 v94, v157, v83
	v_lshl_add_u64 v[80:81], s[30:31], 0, v[188:189]
	v_lshl_add_u64 v[92:93], v[180:181], 1, v[80:81]
	v_cvt_pk_bf16_f32 v82, v84, v85
	v_cvt_pk_bf16_f32 v84, v100, v101
	s_waitcnt lgkmcnt(0)
	v_add_f32_e32 v80, v83, v94
	ds_bpermute_b32 v81, v194, v80
	v_cvt_pk_bf16_f32 v83, v86, v87
	v_cvt_pk_bf16_f32 v85, v104, v105
	global_store_dwordx4 v[92:93], v[88:91], off
	global_store_dwordx4 v[92:93], v[82:85], off offset:256
	s_and_saveexec_b64 s[34:35], vcc
	s_cbranch_execz .LBB0_506
	s_waitcnt lgkmcnt(0)
	v_add_f32_e32 v80, v80, v81
	v_mul_f32_e32 v80, 0x49800000, v80
	v_trunc_f32_e32 v80, v80
	v_mul_f32_e64 v81, |v80|, s70
	v_floor_f32_e32 v81, v81
	v_fma_f32 v82, v81, s71, |v80|
	v_cvt_u32_f32_e32 v82, v82
	v_cvt_u32_f32_e32 v81, v81
	v_ashrrev_i32_e32 v83, 31, v80
	v_xor_b32_e32 v80, v82, v83
	v_xor_b32_e32 v81, v81, v83
	v_sub_co_u32_e64 v80, s[2:3], v80, v83
	s_nop 1
	v_subb_co_u32_e64 v81, s[2:3], v81, v83, s[2:3]
	global_atomic_add_x2 v[112:113], v[80:81], off offset:256
.LBB0_506:
	s_or_b64 exec, exec, s[34:35]
	v_lshlrev_b32_e32 v80, 16, v132
	s_waitcnt lgkmcnt(0)
	v_and_b32_e32 v81, 0xffff0000, v132
	v_lshlrev_b32_e32 v82, 16, v133
	v_and_b32_e32 v83, 0xffff0000, v133
	v_pk_fma_f32 v[76:77], v[174:175], v[76:77], v[80:81]
	v_pk_fma_f32 v[78:79], v[174:175], v[78:79], v[82:83]
	v_lshlrev_b32_e32 v84, 16, v134
	v_and_b32_e32 v85, 0xffff0000, v134
	v_pk_mul_f32 v[80:81], v[76:77], v[76:77]
	v_pk_mul_f32 v[82:83], v[78:79], v[78:79]
	v_pk_fma_f32 v[84:85], v[174:175], v[72:73], v[84:85]
	v_lshlrev_b32_e32 v72, 16, v135
	v_and_b32_e32 v73, 0xffff0000, v135
	v_pk_mul_f32 v[86:87], v[84:85], v[84:85]
	v_pk_fma_f32 v[88:89], v[174:175], v[74:75], v[72:73]
	v_cvt_pk_bf16_f32 v72, v76, v77
	v_lshlrev_b32_e32 v76, 16, v128
	v_and_b32_e32 v77, 0xffff0000, v128
	v_add_f32_e32 v82, v83, v82
	v_add_f32_e32 v80, v81, v80
	v_pk_mul_f32 v[90:91], v[88:89], v[88:89]
	v_cvt_pk_bf16_f32 v73, v78, v79
	v_pk_fma_f32 v[68:69], v[174:175], v[68:69], v[76:77]
	v_lshlrev_b32_e32 v78, 16, v129
	v_and_b32_e32 v79, 0xffff0000, v129
	v_add_f32_e32 v80, v80, v82
	v_add_f32_e32 v81, v87, v86
	v_cvt_pk_bf16_f32 v74, v84, v85
	v_pk_mul_f32 v[76:77], v[68:69], v[68:69]
	v_pk_fma_f32 v[70:71], v[174:175], v[70:71], v[78:79]
	v_lshlrev_b32_e32 v84, 16, v130
	v_and_b32_e32 v85, 0xffff0000, v130
	v_add_f32_e32 v90, v91, v90
	v_add_f32_e32 v80, v81, v80
	v_cvt_pk_bf16_f32 v75, v88, v89
	v_pk_mul_f32 v[78:79], v[70:71], v[70:71]
	v_pk_fma_f32 v[84:85], v[174:175], v[64:65], v[84:85]
	v_lshlrev_b32_e32 v88, 16, v131
	v_and_b32_e32 v89, 0xffff0000, v131
	v_add_f32_e32 v80, v90, v80
	v_add_f32_e32 v76, v77, v76
	v_pk_mul_f32 v[64:65], v[84:85], v[84:85]
	v_pk_fma_f32 v[88:89], v[174:175], v[66:67], v[88:89]
	v_add_f32_e32 v76, v76, v80
	v_add_f32_e32 v77, v79, v78
	v_pk_mul_f32 v[66:67], v[88:89], v[88:89]
	v_add_f32_e32 v76, v77, v76
	v_add_f32_e32 v64, v65, v64
	v_add_f32_e32 v64, v64, v76
	v_add_f32_e32 v65, v67, v66
	v_add_f32_e32 v67, v65, v64
	ds_bpermute_b32 v78, v157, v67
	v_lshl_add_u64 v[64:65], s[30:31], 0, v[186:187]
	v_lshl_add_u64 v[76:77], v[180:181], 1, v[64:65]
	v_cvt_pk_bf16_f32 v66, v68, v69
	v_cvt_pk_bf16_f32 v68, v84, v85
	s_waitcnt lgkmcnt(0)
	v_add_f32_e32 v64, v67, v78
	ds_bpermute_b32 v65, v194, v64
	v_cvt_pk_bf16_f32 v67, v70, v71
	v_cvt_pk_bf16_f32 v69, v88, v89
	global_store_dwordx4 v[76:77], v[72:75], off
	global_store_dwordx4 v[76:77], v[66:69], off offset:256
	s_and_saveexec_b64 s[34:35], vcc
	s_cbranch_execz .LBB0_508
	s_waitcnt lgkmcnt(0)
	v_add_f32_e32 v64, v64, v65
	v_mul_f32_e32 v64, 0x49800000, v64
	v_trunc_f32_e32 v64, v64
	v_mul_f32_e64 v65, |v64|, s70
	v_floor_f32_e32 v65, v65
	v_fma_f32 v66, v65, s71, |v64|
	v_cvt_u32_f32_e32 v66, v66
	v_cvt_u32_f32_e32 v65, v65
	v_ashrrev_i32_e32 v67, 31, v64
	v_xor_b32_e32 v64, v66, v67
	v_xor_b32_e32 v65, v65, v67
	v_sub_co_u32_e64 v64, s[2:3], v64, v67
	s_nop 1
	v_subb_co_u32_e64 v65, s[2:3], v65, v67, s[2:3]
	global_atomic_add_x2 v[112:113], v[64:65], off offset:384
.LBB0_508:
	s_or_b64 exec, exec, s[34:35]
	s_mov_b64 s[2:3], 0x40000
	v_lshl_add_u64 v[102:103], v[184:185], 0, s[2:3]
	s_waitcnt lgkmcnt(0)
	v_lshl_add_u64 v[64:65], v[182:183], 0, v[102:103]
	global_load_dwordx4 v[94:97], v[64:65], off
	global_load_dwordx4 v[98:101], v[64:65], off offset:256
	s_mov_b64 s[2:3], 0x48000
	v_lshl_add_u64 v[92:93], v[184:185], 0, s[2:3]
	s_mov_b64 s[2:3], 0x50000
	v_lshl_add_u64 v[64:65], v[182:183], 0, v[92:93]
	v_lshl_add_u64 v[90:91], v[184:185], 0, s[2:3]
	s_mov_b64 s[2:3], 0x58000
	global_load_dwordx4 v[84:87], v[64:65], off
	global_load_dwordx4 v[80:83], v[64:65], off offset:256
	v_lshl_add_u64 v[64:65], v[182:183], 0, v[90:91]
	v_lshl_add_u64 v[88:89], v[184:185], 0, s[2:3]
	global_load_dwordx4 v[76:79], v[64:65], off
	global_load_dwordx4 v[72:75], v[64:65], off offset:256
	v_lshl_add_u64 v[64:65], v[182:183], 0, v[88:89]
	global_load_dwordx4 v[68:71], v[64:65], off
	s_nop 0
	global_load_dwordx4 v[64:67], v[64:65], off offset:256
	s_waitcnt vmcnt(7)
	v_lshlrev_b32_e32 v104, 16, v94
	v_and_b32_e32 v105, 0xffff0000, v94
	v_lshlrev_b32_e32 v106, 16, v96
	v_and_b32_e32 v107, 0xffff0000, v96
	v_pk_fma_f32 v[60:61], v[174:175], v[60:61], v[104:105]
	v_lshlrev_b32_e32 v94, 16, v95
	v_and_b32_e32 v95, 0xffff0000, v95
	v_pk_fma_f32 v[106:107], v[174:175], v[56:57], v[106:107]
	v_lshlrev_b32_e32 v56, 16, v97
	v_and_b32_e32 v57, 0xffff0000, v97
	v_pk_mul_f32 v[104:105], v[60:61], v[60:61]
	v_pk_fma_f32 v[62:63], v[174:175], v[62:63], v[94:95]
	v_pk_fma_f32 v[96:97], v[174:175], v[58:59], v[56:57]
	v_cvt_pk_bf16_f32 v56, v60, v61
	v_lshl_add_u64 v[60:61], s[30:31], 0, v[102:103]
	v_pk_mul_f32 v[94:95], v[62:63], v[62:63]
	v_cvt_pk_bf16_f32 v57, v62, v63
	v_cvt_pk_bf16_f32 v58, v106, v107
	v_cvt_pk_bf16_f32 v59, v96, v97
	v_lshl_add_u64 v[60:61], v[180:181], 1, v[60:61]
	v_pk_mul_f32 v[108:109], v[106:107], v[106:107]
	global_store_dwordx4 v[60:61], v[56:59], off
	v_add_f32_e32 v94, v95, v94
	v_add_f32_e32 v95, v105, v104
	s_waitcnt vmcnt(7)
	v_lshlrev_b32_e32 v56, 16, v98
	v_and_b32_e32 v57, 0xffff0000, v98
	v_pk_mul_f32 v[110:111], v[96:97], v[96:97]
	v_pk_fma_f32 v[52:53], v[174:175], v[52:53], v[56:57]
	v_lshlrev_b32_e32 v58, 16, v99
	v_and_b32_e32 v59, 0xffff0000, v99
	v_add_f32_e32 v94, v95, v94
	v_add_f32_e32 v95, v109, v108
	v_pk_mul_f32 v[56:57], v[52:53], v[52:53]
	v_pk_fma_f32 v[54:55], v[174:175], v[54:55], v[58:59]
	v_lshlrev_b32_e32 v62, 16, v100
	v_and_b32_e32 v63, 0xffff0000, v100
	v_add_f32_e32 v94, v95, v94
	v_add_f32_e32 v95, v111, v110
	v_pk_mul_f32 v[58:59], v[54:55], v[54:55]
	v_pk_fma_f32 v[62:63], v[174:175], v[48:49], v[62:63]
	v_lshlrev_b32_e32 v96, 16, v101
	v_and_b32_e32 v97, 0xffff0000, v101
	v_add_f32_e32 v94, v95, v94
	v_add_f32_e32 v56, v57, v56
	v_pk_mul_f32 v[48:49], v[62:63], v[62:63]
	v_pk_fma_f32 v[96:97], v[174:175], v[50:51], v[96:97]
	v_add_f32_e32 v56, v56, v94
	v_add_f32_e32 v57, v59, v58
	v_pk_mul_f32 v[50:51], v[96:97], v[96:97]
	v_add_f32_e32 v56, v57, v56
	v_add_f32_e32 v48, v49, v48
	v_add_f32_e32 v48, v48, v56
	v_add_f32_e32 v49, v51, v50
	v_add_f32_e32 v56, v49, v48
	v_cvt_pk_bf16_f32 v48, v52, v53
	v_cvt_pk_bf16_f32 v49, v54, v55
	v_cvt_pk_bf16_f32 v50, v62, v63
	v_cvt_pk_bf16_f32 v51, v96, v97
	global_store_dwordx4 v[60:61], v[48:51], off offset:256
	ds_bpermute_b32 v48, v157, v56
	s_waitcnt lgkmcnt(0)
	v_add_f32_e32 v48, v56, v48
	ds_bpermute_b32 v49, v194, v48
	s_and_saveexec_b64 s[34:35], vcc
	s_cbranch_execz .LBB0_510
	s_waitcnt lgkmcnt(0)
	v_add_f32_e32 v48, v48, v49
	v_mul_f32_e32 v48, 0x49800000, v48
	v_trunc_f32_e32 v48, v48
	v_mul_f32_e64 v49, |v48|, s70
	v_floor_f32_e32 v49, v49
	v_fma_f32 v50, v49, s71, |v48|
	v_cvt_u32_f32_e32 v50, v50
	v_cvt_u32_f32_e32 v49, v49
	v_ashrrev_i32_e32 v51, 31, v48
	v_xor_b32_e32 v48, v50, v51
	v_xor_b32_e32 v49, v49, v51
	v_sub_co_u32_e64 v48, s[2:3], v48, v51
	s_nop 1
	v_subb_co_u32_e64 v49, s[2:3], v49, v51, s[2:3]
	global_atomic_add_x2 v[112:113], v[48:49], off offset:1024
.LBB0_510:
	s_or_b64 exec, exec, s[34:35]
	s_waitcnt vmcnt(7)
	v_lshlrev_b32_e32 v48, 16, v84
	s_waitcnt lgkmcnt(0)
	v_and_b32_e32 v49, 0xffff0000, v84
	v_lshlrev_b32_e32 v50, 16, v85
	v_and_b32_e32 v51, 0xffff0000, v85
	v_pk_fma_f32 v[44:45], v[174:175], v[44:45], v[48:49]
	v_pk_fma_f32 v[46:47], v[174:175], v[46:47], v[50:51]
	v_lshlrev_b32_e32 v52, 16, v86
	v_and_b32_e32 v53, 0xffff0000, v86
	v_pk_mul_f32 v[48:49], v[44:45], v[44:45]
	v_pk_mul_f32 v[50:51], v[46:47], v[46:47]
	v_pk_fma_f32 v[52:53], v[174:175], v[40:41], v[52:53]
	v_lshlrev_b32_e32 v40, 16, v87
	v_and_b32_e32 v41, 0xffff0000, v87
	v_pk_mul_f32 v[54:55], v[52:53], v[52:53]
	v_pk_fma_f32 v[56:57], v[174:175], v[42:43], v[40:41]
	v_cvt_pk_bf16_f32 v40, v44, v45
	s_waitcnt vmcnt(6)
	v_lshlrev_b32_e32 v44, 16, v80
	v_and_b32_e32 v45, 0xffff0000, v80
	v_add_f32_e32 v50, v51, v50
	v_add_f32_e32 v48, v49, v48
	v_pk_mul_f32 v[58:59], v[56:57], v[56:57]
	v_cvt_pk_bf16_f32 v41, v46, v47
	v_pk_fma_f32 v[36:37], v[174:175], v[36:37], v[44:45]
	v_lshlrev_b32_e32 v46, 16, v81
	v_and_b32_e32 v47, 0xffff0000, v81
	v_add_f32_e32 v48, v48, v50
	v_add_f32_e32 v49, v55, v54
	v_cvt_pk_bf16_f32 v42, v52, v53
	v_pk_mul_f32 v[44:45], v[36:37], v[36:37]
	v_pk_fma_f32 v[38:39], v[174:175], v[38:39], v[46:47]
	v_lshlrev_b32_e32 v52, 16, v82
	v_and_b32_e32 v53, 0xffff0000, v82
	v_add_f32_e32 v58, v59, v58
	v_add_f32_e32 v48, v49, v48
	v_cvt_pk_bf16_f32 v43, v56, v57
	v_pk_mul_f32 v[46:47], v[38:39], v[38:39]
	v_pk_fma_f32 v[52:53], v[174:175], v[32:33], v[52:53]
	v_lshlrev_b32_e32 v56, 16, v83
	v_and_b32_e32 v57, 0xffff0000, v83
	v_add_f32_e32 v48, v58, v48
	v_add_f32_e32 v44, v45, v44
	v_pk_mul_f32 v[32:33], v[52:53], v[52:53]
	v_pk_fma_f32 v[56:57], v[174:175], v[34:35], v[56:57]
	v_add_f32_e32 v44, v44, v48
	v_add_f32_e32 v45, v47, v46
	v_pk_mul_f32 v[34:35], v[56:57], v[56:57]
	v_add_f32_e32 v44, v45, v44
	v_add_f32_e32 v32, v33, v32
	v_add_f32_e32 v32, v32, v44
	v_add_f32_e32 v33, v35, v34
	v_add_f32_e32 v35, v33, v32
	ds_bpermute_b32 v46, v157, v35
	v_lshl_add_u64 v[32:33], s[30:31], 0, v[92:93]
	v_lshl_add_u64 v[44:45], v[180:181], 1, v[32:33]
	v_cvt_pk_bf16_f32 v34, v36, v37
	v_cvt_pk_bf16_f32 v36, v52, v53
	s_waitcnt lgkmcnt(0)
	v_add_f32_e32 v32, v35, v46
	ds_bpermute_b32 v33, v194, v32
	v_cvt_pk_bf16_f32 v35, v38, v39
	v_cvt_pk_bf16_f32 v37, v56, v57
	global_store_dwordx4 v[44:45], v[40:43], off
	global_store_dwordx4 v[44:45], v[34:37], off offset:256
	s_and_saveexec_b64 s[34:35], vcc
	s_cbranch_execz .LBB0_512
	s_waitcnt lgkmcnt(0)
	v_add_f32_e32 v32, v32, v33
	v_mul_f32_e32 v32, 0x49800000, v32
	v_trunc_f32_e32 v32, v32
	v_mul_f32_e64 v33, |v32|, s70
	v_floor_f32_e32 v33, v33
	v_fma_f32 v34, v33, s71, |v32|
	v_cvt_u32_f32_e32 v34, v34
	v_cvt_u32_f32_e32 v33, v33
	v_ashrrev_i32_e32 v35, 31, v32
	v_xor_b32_e32 v32, v34, v35
	v_xor_b32_e32 v33, v33, v35
	v_sub_co_u32_e64 v32, s[2:3], v32, v35
	s_nop 1
	v_subb_co_u32_e64 v33, s[2:3], v33, v35, s[2:3]
	global_atomic_add_x2 v[112:113], v[32:33], off offset:1152
.LBB0_512:
	s_or_b64 exec, exec, s[34:35]
	s_waitcnt vmcnt(7)
	v_lshlrev_b32_e32 v32, 16, v76
	s_waitcnt lgkmcnt(0)
	v_and_b32_e32 v33, 0xffff0000, v76
	v_lshlrev_b32_e32 v34, 16, v77
	v_and_b32_e32 v35, 0xffff0000, v77
	v_pk_fma_f32 v[28:29], v[174:175], v[28:29], v[32:33]
	v_pk_fma_f32 v[30:31], v[174:175], v[30:31], v[34:35]
	v_lshlrev_b32_e32 v36, 16, v78
	v_and_b32_e32 v37, 0xffff0000, v78
	v_pk_mul_f32 v[32:33], v[28:29], v[28:29]
	v_pk_mul_f32 v[34:35], v[30:31], v[30:31]
	v_pk_fma_f32 v[36:37], v[174:175], v[24:25], v[36:37]
	v_lshlrev_b32_e32 v24, 16, v79
	v_and_b32_e32 v25, 0xffff0000, v79
	v_pk_mul_f32 v[38:39], v[36:37], v[36:37]
	v_pk_fma_f32 v[40:41], v[174:175], v[26:27], v[24:25]
	v_cvt_pk_bf16_f32 v24, v28, v29
	s_waitcnt vmcnt(6)
	v_lshlrev_b32_e32 v28, 16, v72
	v_and_b32_e32 v29, 0xffff0000, v72
	v_add_f32_e32 v34, v35, v34
	v_add_f32_e32 v32, v33, v32
	v_pk_mul_f32 v[42:43], v[40:41], v[40:41]
	v_cvt_pk_bf16_f32 v25, v30, v31
	v_pk_fma_f32 v[20:21], v[174:175], v[20:21], v[28:29]
	v_lshlrev_b32_e32 v30, 16, v73
	v_and_b32_e32 v31, 0xffff0000, v73
	v_add_f32_e32 v32, v32, v34
	v_add_f32_e32 v33, v39, v38
	v_cvt_pk_bf16_f32 v26, v36, v37
	v_pk_mul_f32 v[28:29], v[20:21], v[20:21]
	v_pk_fma_f32 v[22:23], v[174:175], v[22:23], v[30:31]
	v_lshlrev_b32_e32 v36, 16, v74
	v_and_b32_e32 v37, 0xffff0000, v74
	v_add_f32_e32 v42, v43, v42
	v_add_f32_e32 v32, v33, v32
	v_cvt_pk_bf16_f32 v27, v40, v41
	v_pk_mul_f32 v[30:31], v[22:23], v[22:23]
	v_pk_fma_f32 v[36:37], v[174:175], v[16:17], v[36:37]
	v_lshlrev_b32_e32 v40, 16, v75
	v_and_b32_e32 v41, 0xffff0000, v75
	v_add_f32_e32 v32, v42, v32
	v_add_f32_e32 v28, v29, v28
	v_pk_mul_f32 v[16:17], v[36:37], v[36:37]
	v_pk_fma_f32 v[40:41], v[174:175], v[18:19], v[40:41]
	v_add_f32_e32 v28, v28, v32
	v_add_f32_e32 v29, v31, v30
	v_pk_mul_f32 v[18:19], v[40:41], v[40:41]
	v_add_f32_e32 v28, v29, v28
	v_add_f32_e32 v16, v17, v16
	v_add_f32_e32 v16, v16, v28
	v_add_f32_e32 v17, v19, v18
	v_add_f32_e32 v19, v17, v16
	ds_bpermute_b32 v30, v157, v19
	v_lshl_add_u64 v[16:17], s[30:31], 0, v[90:91]
	v_lshl_add_u64 v[28:29], v[180:181], 1, v[16:17]
	v_cvt_pk_bf16_f32 v18, v20, v21
	v_cvt_pk_bf16_f32 v20, v36, v37
	s_waitcnt lgkmcnt(0)
	v_add_f32_e32 v16, v19, v30
	ds_bpermute_b32 v17, v194, v16
	v_cvt_pk_bf16_f32 v19, v22, v23
	v_cvt_pk_bf16_f32 v21, v40, v41
	global_store_dwordx4 v[28:29], v[24:27], off
	global_store_dwordx4 v[28:29], v[18:21], off offset:256
	s_and_saveexec_b64 s[34:35], vcc
	s_cbranch_execz .LBB0_514
	s_waitcnt lgkmcnt(0)
	v_add_f32_e32 v16, v16, v17
	v_mul_f32_e32 v16, 0x49800000, v16
	v_trunc_f32_e32 v16, v16
	v_mul_f32_e64 v17, |v16|, s70
	v_floor_f32_e32 v17, v17
	v_fma_f32 v18, v17, s71, |v16|
	v_cvt_u32_f32_e32 v18, v18
	v_cvt_u32_f32_e32 v17, v17
	v_ashrrev_i32_e32 v19, 31, v16
	v_xor_b32_e32 v16, v18, v19
	v_xor_b32_e32 v17, v17, v19
	v_sub_co_u32_e64 v16, s[2:3], v16, v19
	s_nop 1
	v_subb_co_u32_e64 v17, s[2:3], v17, v19, s[2:3]
	global_atomic_add_x2 v[112:113], v[16:17], off offset:1280
.LBB0_514:
	s_or_b64 exec, exec, s[34:35]
	s_waitcnt vmcnt(7)
	v_lshlrev_b32_e32 v16, 16, v68
	s_waitcnt lgkmcnt(0)
	v_and_b32_e32 v17, 0xffff0000, v68
	v_lshlrev_b32_e32 v18, 16, v69
	v_and_b32_e32 v19, 0xffff0000, v69
	v_pk_fma_f32 v[12:13], v[174:175], v[12:13], v[16:17]
	v_pk_fma_f32 v[14:15], v[174:175], v[14:15], v[18:19]
	v_lshlrev_b32_e32 v20, 16, v70
	v_and_b32_e32 v21, 0xffff0000, v70
	v_pk_mul_f32 v[16:17], v[12:13], v[12:13]
	v_pk_mul_f32 v[18:19], v[14:15], v[14:15]
	v_pk_fma_f32 v[20:21], v[174:175], v[8:9], v[20:21]
	v_lshlrev_b32_e32 v8, 16, v71
	v_and_b32_e32 v9, 0xffff0000, v71
	v_pk_mul_f32 v[22:23], v[20:21], v[20:21]
	v_pk_fma_f32 v[24:25], v[174:175], v[10:11], v[8:9]
	v_cvt_pk_bf16_f32 v8, v12, v13
	s_waitcnt vmcnt(6)
	v_lshlrev_b32_e32 v12, 16, v64
	v_and_b32_e32 v13, 0xffff0000, v64
	v_add_f32_e32 v18, v19, v18
	v_add_f32_e32 v16, v17, v16
	v_pk_mul_f32 v[26:27], v[24:25], v[24:25]
	v_cvt_pk_bf16_f32 v9, v14, v15
	v_pk_fma_f32 v[4:5], v[174:175], v[4:5], v[12:13]
	v_lshlrev_b32_e32 v14, 16, v65
	v_and_b32_e32 v15, 0xffff0000, v65
	v_add_f32_e32 v16, v16, v18
	v_add_f32_e32 v17, v23, v22
	v_cvt_pk_bf16_f32 v10, v20, v21
	v_pk_mul_f32 v[12:13], v[4:5], v[4:5]
	v_pk_fma_f32 v[6:7], v[174:175], v[6:7], v[14:15]
	v_lshlrev_b32_e32 v20, 16, v66
	v_and_b32_e32 v21, 0xffff0000, v66
	v_add_f32_e32 v26, v27, v26
	v_add_f32_e32 v16, v17, v16
	v_cvt_pk_bf16_f32 v11, v24, v25
	v_pk_mul_f32 v[14:15], v[6:7], v[6:7]
	v_pk_fma_f32 v[20:21], v[174:175], v[0:1], v[20:21]
	v_lshlrev_b32_e32 v24, 16, v67
	v_and_b32_e32 v25, 0xffff0000, v67
	v_add_f32_e32 v16, v26, v16
	v_add_f32_e32 v12, v13, v12
	v_pk_mul_f32 v[0:1], v[20:21], v[20:21]
	v_pk_fma_f32 v[24:25], v[174:175], v[2:3], v[24:25]
	v_add_f32_e32 v12, v12, v16
	v_add_f32_e32 v13, v15, v14
	v_pk_mul_f32 v[2:3], v[24:25], v[24:25]
	v_add_f32_e32 v12, v13, v12
	v_add_f32_e32 v0, v1, v0
	v_add_f32_e32 v0, v0, v12
	v_add_f32_e32 v1, v3, v2
	v_add_f32_e32 v3, v1, v0
	ds_bpermute_b32 v14, v157, v3
	v_lshl_add_u64 v[0:1], s[30:31], 0, v[88:89]
	v_lshl_add_u64 v[12:13], v[180:181], 1, v[0:1]
	v_cvt_pk_bf16_f32 v2, v4, v5
	v_cvt_pk_bf16_f32 v4, v20, v21
	s_waitcnt lgkmcnt(0)
	v_add_f32_e32 v0, v3, v14
	ds_bpermute_b32 v1, v194, v0
	v_cvt_pk_bf16_f32 v3, v6, v7
	v_cvt_pk_bf16_f32 v5, v24, v25
	global_store_dwordx4 v[12:13], v[8:11], off
	global_store_dwordx4 v[12:13], v[2:5], off offset:256
	s_and_saveexec_b64 s[2:3], vcc
	s_cbranch_execz .LBB0_516
	s_waitcnt lgkmcnt(0)
	v_add_f32_e32 v0, v0, v1
	v_mul_f32_e32 v0, 0x49800000, v0
	v_trunc_f32_e32 v0, v0
	v_mul_f32_e64 v1, |v0|, s70
	v_floor_f32_e32 v1, v1
	v_fma_f32 v2, v1, s71, |v0|
	v_cvt_u32_f32_e32 v2, v2
	v_cvt_u32_f32_e32 v1, v1
	v_ashrrev_i32_e32 v3, 31, v0
	v_xor_b32_e32 v0, v2, v3
	v_xor_b32_e32 v1, v1, v3
	v_sub_co_u32_e32 v0, vcc, v0, v3
	s_nop 1
	v_subb_co_u32_e32 v1, vcc, v1, v3, vcc
	global_atomic_add_x2 v[112:113], v[0:1], off offset:1408

.LBB0_621:
	v_ashrrev_i32_e32 v2, 31, v0
	v_lshrrev_b32_e32 v2, 26, v2
	v_lshlrev_b32_e32 v1, 4, v0
	v_add_u32_e32 v2, v0, v2
	v_bfe_i32 v0, v0, 27, 1
	v_lshrrev_b32_e32 v0, 22, v0
	v_add_u32_e32 v0, v1, v0
	v_and_b32_e32 v0, 0xfffffc00, v0
	v_sub_u32_e32 v0, v1, v0
	v_ashrrev_i32_e32 v9, 6, v2
	v_lshrrev_b32_e32 v2, 4, v0
	v_bitop3_b32 v0, v2, v0, 32 bitop3:0x6c
	v_ashrrev_i32_e32 v3, 31, v0
	v_lshrrev_b32_e32 v3, 26, v3
	v_add_u32_e32 v3, v0, v3
	v_lshlrev_b32_e32 v2, 3, v9
	v_ashrrev_i32_e32 v10, 6, v3
	v_and_b32_e32 v3, 0xc0, v3
	v_and_b32_e32 v2, -16, v2
	v_sub_u32_e32 v0, v0, v3
	v_add_u32_e32 v2, v10, v2
	v_ashrrev_i16_sdwa v0, v196, sext(v0) dst_sel:DWORD dst_unused:UNUSED_PAD src0_sel:DWORD src1_sel:BYTE_0
	v_lshlrev_b32_e32 v4, 5, v9
	v_bfe_i32 v11, v0, 0, 16
	v_lshlrev_b32_e32 v0, 1, v2
	v_lshrrev_b32_e32 v3, 2, v2
	v_and_b32_e32 v5, 3, v10
	s_mov_b32 s0, 0x1fffe0
	v_and_b32_e32 v4, 32, v4
	v_and_b32_e32 v0, 24, v0
	v_and_b32_e32 v3, 4, v3
	v_and_or_b32 v5, v2, s0, v5
	v_or3_b32 v0, v5, v3, v0
	v_add_lshl_u32 v3, v4, v11, 1
	s_nop 0
	v_add_u32_e32 v0, 0x2000, v1
	v_ashrrev_i32_e32 v1, 31, v0
	v_lshrrev_b32_e32 v1, 22, v1
	v_add_u32_e32 v1, v0, v1
	v_ashrrev_i32_e32 v12, 10, v1
	v_mul_i32_i24_e32 v1, 0x400, v12
	v_sub_u32_e32 v0, v0, v1
	v_lshrrev_b32_e32 v1, 4, v0
	v_bitop3_b32 v0, v1, v0, 32 bitop3:0x6c
	s_nop 0
	v_ashrrev_i32_e32 v2, 31, v0
	v_lshrrev_b32_e32 v2, 26, v2
	v_lshlrev_b32_e32 v1, 3, v12
	v_add_u32_e32 v2, v0, v2
	v_and_b32_e32 v1, -16, v1
	v_ashrrev_i32_e32 v13, 6, v2
	s_ashr_i32 s6, s4, 6
	s_ashr_i32 s5, s4, 8
	v_add_u32_e32 v1, v13, v1
	v_and_b32_e32 v4, 3, v13
	s_lshl_b32 s48, s6, 10
	v_and_or_b32 v4, v1, s0, v4
	s_and_b64 s[0:1], s[2:3], exec
	s_cselect_b32 s0, 0, 0x1380000
	s_add_u32 s49, s51, s0
	v_readlane_b32 s0, v241, 60
	v_and_b32_e32 v2, 0xc0, v2
	s_addc_u32 s50, s0, 0
	s_ashr_i32 s29, s28, 31
	s_ashr_i32 s17, s16, 31
	v_sub_u32_e32 v0, v0, v2
	s_lshl_b64 s[0:1], s[28:29], 19
	s_lshl_b64 s[2:3], s[16:17], 19
	v_ashrrev_i16_sdwa v0, v196, sext(v0) dst_sel:DWORD dst_unused:UNUSED_PAD src0_sel:DWORD src1_sel:BYTE_0
	s_add_u32 s40, s49, s2
	v_lshlrev_b32_e32 v3, 5, v12
	v_bfe_i32 v14, v0, 0, 16
	v_lshlrev_b32_e32 v0, 1, v1
	v_lshrrev_b32_e32 v2, 2, v1
	s_addc_u32 s41, s50, s3
	s_add_i32 s51, s48, 0
	v_and_b32_e32 v3, 32, v3
	v_and_b32_e32 v0, 24, v0
	v_and_b32_e32 v2, 4, v2
	s_lshr_b32 s86, s4, 6
	s_and_b32 s87, s86, 1
	s_lshl_b32 s87, s87, 2
	v_lshrrev_b32_e32 v243, 4, v8
	v_or_b32_e32 v243, s87, v243
	v_and_b32_e32 v244, 7, v8
	v_xor_b32_e32 v243, v244, v243
	v_lshlrev_b32_e32 v243, 4, v243
	v_lshrrev_b32_e32 v244, 3, v8
	s_lshl_b32 s86, s86, 3
	v_add_u32_e32 v244, s86, v244
	v_lshl_add_u32 v132, v244, 11, v243
	v_add_u32_e32 v136, 0x20000, v132
	v_and_b32_e32 v245, 31, v244
	v_bfe_u32 v246, v245, 2, 2
	v_lshlrev_b32_e32 v246, 3, v246
	v_bfe_u32 v247, v245, 4, 1
	v_lshl_or_b32 v246, v247, 2, v246
	v_and_b32_e32 v247, 3, v245
	v_or_b32_e32 v246, v246, v247
	v_and_b32_e32 v247, 0xffffffe0, v244
	v_or_b32_e32 v246, v247, v246
	v_lshl_add_u32 v134, v246, 11, v243
	v_add_u32_e32 v138, 0x20000, v134
	v_and_b32_e32 v245, 15, v8
	v_lshrrev_b32_e32 v246, 4, v8
	v_lshrrev_b32_e32 v247, 1, v245
	v_xor_b32_e32 v246, v246, v247
	v_lshlrev_b32_e32 v246, 4, v246
	v_lshl_or_b32 v246, v245, 7, v246
	s_lshr_b32 s86, s4, 8
	s_lshl_b32 s86, s86, 13
	v_or_b32_e32 v173, s86, v246
	v_xor_b32_e32 v244, 64, v173
	s_lshr_b32 s86, s4, 6
	s_and_b32 s86, s86, 3
	s_lshl_b32 s86, s86, 12
	v_or_b32_e32 v172, s86, v246
	v_xor_b32_e32 v243, 64, v172
	s_add_i32 m0, s51, 0x10000
	v_or3_b32 v0, v4, v2, v0
	v_add_lshl_u32 v2, v3, v14, 1
	global_load_lds_dwordx4 v134, s[40:41]
	s_add_i32 m0, s51, 0x12000
	s_nop 0
	s_add_u32 s2, s40, 0x40000
	global_load_lds_dwordx4 v138, s[40:41]
	s_addc_u32 s3, s41, 0
	s_add_i32 m0, s51, 0x14000
	s_nop 0
	global_load_lds_dwordx4 v134, s[2:3]
	s_add_i32 m0, s51, 0x16000
	s_add_u32 s34, s30, s0
	s_addc_u32 s35, s31, s1
	s_add_i32 s60, s51, 0x2000
	global_load_lds_dwordx4 v138, s[2:3]
	s_mov_b32 m0, s51
	s_add_u32 s0, s34, 0x40000
	global_load_lds_dwordx4 v132, s[34:35]
	s_mov_b32 m0, s60
	s_addc_u32 s1, s35, 0
	s_add_i32 s61, s51, 0x4000
	global_load_lds_dwordx4 v136, s[34:35]
	s_mov_b32 m0, s61
	s_add_i32 s64, s51, 0x6000
	global_load_lds_dwordx4 v132, s[0:1]
	s_mov_b32 m0, s64
	v_mov_b32_e32 v135, v159
	global_load_lds_dwordx4 v136, s[0:1]
	v_mov_b32_e32 v139, v159
	v_mov_b32_e32 v133, v159
	v_mov_b32_e32 v137, v159
	s_cmp_eq_u32 s5, 1
	v_lshl_add_u64 v[6:7], s[40:41], 0, v[134:135]
	v_lshl_add_u64 v[4:5], s[40:41], 0, v[138:139]
	v_lshl_add_u64 v[0:1], s[34:35], 0, v[132:133]
	s_cselect_b64 s[0:1], -1, 0
	s_cmp_lg_u32 s5, 1
	v_lshl_add_u64 v[2:3], s[34:35], 0, v[136:137]
	s_cbranch_scc1 .LBB0_623
	s_barrier
.LBB0_623:
	s_lshl_b32 s2, s6, 5
	s_and_b32 s75, s2, 0x60
	s_add_i32 m0, s51, 0x18000
	v_lshl_add_u64 v[6:7], v[6:7], 0, s[14:15]
	s_lshl_b32 s65, s5, 6
	s_lshl_b32 s5, s5, 13
	s_lshl_b32 s6, s75, 7
	s_waitcnt vmcnt(2)
	s_barrier
	global_load_lds_dwordx4 v[6:7], off
	v_lshl_add_u64 v[4:5], v[4:5], 0, s[14:15]
	s_add_i32 m0, s51, 0x1a000
	s_add_i32 s76, s51, 0x8000
	s_add_i32 s77, s51, 0xa000
	global_load_lds_dwordx4 v[4:5], off
	v_lshl_add_u64 v[0:1], v[0:1], 0, s[14:15]
	s_mov_b32 m0, s76
	s_add_u32 s2, s40, 0x40080
	global_load_lds_dwordx4 v[0:1], off
	v_lshl_add_u64 v[0:1], v[2:3], 0, s[14:15]
	s_mov_b32 m0, s77
	s_addc_u32 s3, s41, 0
	global_load_lds_dwordx4 v[0:1], off
	s_add_i32 m0, s51, 0x1c000
	v_lshl_add_u64 v[0:1], s[2:3], 0, v[134:135]
	global_load_lds_dwordx4 v[0:1], off
	v_lshl_add_u64 v[0:1], s[2:3], 0, v[138:139]
	s_add_i32 m0, s51, 0x1e000
	v_bfe_u32 v171, v8, 4, 2
	global_load_lds_dwordx4 v[0:1], off
	v_and_b32_e32 v170, 15, v8
	v_lshlrev_b32_e32 v0, 4, v171
	v_lshlrev_b32_e32 v1, 2, v8
	v_lshl_or_b32 v0, v170, 6, v0
	v_and_b32_e32 v1, 32, v1
	v_bitop3_b32 v2, v0, s5, v1 bitop3:0xde
	s_nop 0
	v_lshlrev_b32_e32 v0, 14, v9
	v_and_b32_e32 v0, 0xffff8000, v0
	v_lshl_add_u32 v0, v10, 11, v0
	v_and_b32_e32 v1, 1, v9
	v_lshl_or_b32 v0, v1, 6, v0
	v_lshl_add_u32 v140, v11, 1, v0
	v_lshlrev_b32_e32 v0, 14, v12
	v_and_b32_e32 v0, 0xffff8000, v0
	s_waitcnt vmcnt(6)
	v_lshl_add_u32 v0, v13, 11, v0
	v_and_b32_e32 v1, 1, v12
	s_cmpk_lt_u32 s4, 0x100
	v_lshl_or_b32 v0, v1, 6, v0
	s_cselect_b64 s[2:3], -1, 0
	s_or_b32 s79, s75, 0xffffea00
	v_mov_b32_e32 v141, v159
	v_lshl_add_u32 v142, v14, 1, v0
	v_mov_b32_e32 v143, v159
	s_mov_b32 s17, 0
	s_nop 0
	s_mov_b32 s80, 0
	s_barrier
	s_branch .LBB0_626

.LBB0_629:
	s_add_u32 s40, s34, 0xfffc0080
	s_addc_u32 s41, s35, -1
	s_add_i32 s62, 0, 0x10000
	s_cmp_eq_u32 s85, 12
	s_cselect_b32 s43, s13, s41
	s_cselect_b32 s42, s29, s40
	s_cselect_b32 s41, s5, s84
	s_cselect_b32 s40, s82, s83
	s_add_i32 s63, 0, 0x14000
	s_add_u32 s86, s34, 0xfffc0000
	s_addc_u32 s87, s35, -1
	s_mov_b32 m0, s76
	v_add_u32_e32 v152, s62, v172
	v_add_u32_e32 v158, s63, v172
	v_add_u32_e32 v245, s62, v243
	v_add_u32_e32 v246, s63, v243
	global_load_lds_dwordx4 v132, s[86:87]
	s_mov_b32 m0, s77
	ds_read_b128 v[128:131], v152
	global_load_lds_dwordx4 v136, s[86:87]
	ds_read_b128 v[144:147], v245
	ds_read_b128 v[148:151], v152 offset:2048
	ds_read_b128 v[152:155], v245 offset:2048
	ds_read_b128 v[174:177], v158
	ds_read_b128 v[178:181], v246
	ds_read_b128 v[182:185], v158 offset:2048
	ds_read_b128 v[186:189], v246 offset:2048
	ds_read_b128 v[190:193], v173
	ds_read_b128 v[198:201], v244
	ds_read_b128 v[202:205], v173 offset:2048
	ds_read_b128 v[206:209], v244 offset:2048
	ds_read_b128 v[210:213], v173 offset:4096
	ds_read_b128 v[214:217], v244 offset:4096
	ds_read_b128 v[218:221], v173 offset:6144
	ds_read_b128 v[222:225], v244 offset:6144
	s_waitcnt vmcnt(6)
	s_waitcnt lgkmcnt(0)
	s_barrier
	s_setprio 1
	s_waitcnt lgkmcnt(0)
	v_mfma_f32_16x16x32_bf16 v[124:127], v[128:131], v[190:193], v[124:127]
	v_mfma_f32_16x16x32_bf16 v[116:119], v[148:151], v[190:193], v[116:119]
	v_mfma_f32_16x16x32_bf16 v[108:111], v[128:131], v[202:205], v[108:111]
	s_add_i32 m0, s51, 0xc000
	v_mfma_f32_16x16x32_bf16 v[100:103], v[148:151], v[202:205], v[100:103]
	v_mfma_f32_16x16x32_bf16 v[92:95], v[128:131], v[210:213], v[92:95]
	global_load_lds_dwordx4 v132, s[34:35]
	v_mfma_f32_16x16x32_bf16 v[84:87], v[148:151], v[210:213], v[84:87]
	v_mfma_f32_16x16x32_bf16 v[76:79], v[128:131], v[218:221], v[76:79]
	v_mfma_f32_16x16x32_bf16 v[68:71], v[148:151], v[218:221], v[68:71]
	v_mfma_f32_16x16x32_bf16 v[124:127], v[144:147], v[198:201], v[124:127]
	v_mfma_f32_16x16x32_bf16 v[116:119], v[152:155], v[198:201], v[116:119]
	v_mfma_f32_16x16x32_bf16 v[108:111], v[144:147], v[206:209], v[108:111]
	s_add_i32 m0, s51, 0xe000
	v_mfma_f32_16x16x32_bf16 v[100:103], v[152:155], v[206:209], v[100:103]
	v_mfma_f32_16x16x32_bf16 v[92:95], v[144:147], v[214:217], v[92:95]
	global_load_lds_dwordx4 v136, s[34:35]
	v_mfma_f32_16x16x32_bf16 v[84:87], v[152:155], v[214:217], v[84:87]
	v_mfma_f32_16x16x32_bf16 v[76:79], v[144:147], v[222:225], v[76:79]
	v_mfma_f32_16x16x32_bf16 v[68:71], v[152:155], v[222:225], v[68:71]
	s_setprio 0
	s_setprio 1
	v_mfma_f32_16x16x32_bf16 v[120:123], v[174:177], v[190:193], v[120:123]
	v_mfma_f32_16x16x32_bf16 v[112:115], v[182:185], v[190:193], v[112:115]
	v_mfma_f32_16x16x32_bf16 v[104:107], v[174:177], v[202:205], v[104:107]
	v_mfma_f32_16x16x32_bf16 v[96:99], v[182:185], v[202:205], v[96:99]
	v_mfma_f32_16x16x32_bf16 v[88:91], v[174:177], v[210:213], v[88:91]
	v_mfma_f32_16x16x32_bf16 v[80:83], v[182:185], v[210:213], v[80:83]
	v_mfma_f32_16x16x32_bf16 v[72:75], v[174:177], v[218:221], v[72:75]
	v_mfma_f32_16x16x32_bf16 v[64:67], v[182:185], v[218:221], v[64:67]
	v_mfma_f32_16x16x32_bf16 v[120:123], v[178:181], v[198:201], v[120:123]
	v_mfma_f32_16x16x32_bf16 v[112:115], v[186:189], v[198:201], v[112:115]
	v_mfma_f32_16x16x32_bf16 v[104:107], v[178:181], v[206:209], v[104:107]
	v_mfma_f32_16x16x32_bf16 v[96:99], v[186:189], v[206:209], v[96:99]
	v_mfma_f32_16x16x32_bf16 v[88:91], v[178:181], v[214:217], v[88:91]
	v_mfma_f32_16x16x32_bf16 v[80:83], v[186:189], v[214:217], v[80:83]
	v_mfma_f32_16x16x32_bf16 v[72:75], v[178:181], v[222:225], v[72:75]
	v_mfma_f32_16x16x32_bf16 v[64:67], v[186:189], v[222:225], v[64:67]
	s_setprio 0
	s_barrier
	s_add_i32 s62, s62, s48
	s_mov_b32 m0, s62
	ds_read_b128 v[190:193], v173 offset:16384
	global_load_lds_dwordx4 v134, s[40:41]
	s_add_i32 m0, s62, 0x2000
	ds_read_b128 v[198:201], v244 offset:16384
	global_load_lds_dwordx4 v138, s[40:41]
	ds_read_b128 v[202:205], v173 offset:18432
	ds_read_b128 v[206:209], v244 offset:18432
	ds_read_b128 v[210:213], v173 offset:20480
	ds_read_b128 v[214:217], v244 offset:20480
	ds_read_b128 v[218:221], v173 offset:22528
	ds_read_b128 v[222:225], v244 offset:22528
	s_add_u32 s86, s40, 0x40000
	s_addc_u32 s87, s41, 0
	s_add_i32 s62, s63, s48
	s_waitcnt vmcnt(4)
	s_waitcnt lgkmcnt(0)
	s_barrier
	s_setprio 1
	s_waitcnt lgkmcnt(0)
	v_mfma_f32_16x16x32_bf16 v[60:63], v[128:131], v[190:193], v[60:63]
	v_mfma_f32_16x16x32_bf16 v[52:55], v[148:151], v[190:193], v[52:55]
	v_mfma_f32_16x16x32_bf16 v[44:47], v[128:131], v[202:205], v[44:47]
	s_mov_b32 m0, s62
	v_mfma_f32_16x16x32_bf16 v[36:39], v[148:151], v[202:205], v[36:39]
	v_mfma_f32_16x16x32_bf16 v[28:31], v[128:131], v[210:213], v[28:31]
	global_load_lds_dwordx4 v134, s[86:87]
	v_mfma_f32_16x16x32_bf16 v[20:23], v[148:151], v[210:213], v[20:23]
	v_mfma_f32_16x16x32_bf16 v[8:11], v[128:131], v[218:221], v[8:11]
	v_mfma_f32_16x16x32_bf16 v[4:7], v[148:151], v[218:221], v[4:7]
	v_mfma_f32_16x16x32_bf16 v[60:63], v[144:147], v[198:201], v[60:63]
	v_mfma_f32_16x16x32_bf16 v[52:55], v[152:155], v[198:201], v[52:55]
	v_mfma_f32_16x16x32_bf16 v[44:47], v[144:147], v[206:209], v[44:47]
	s_add_i32 m0, s62, 0x2000
	v_mfma_f32_16x16x32_bf16 v[36:39], v[152:155], v[206:209], v[36:39]
	v_mfma_f32_16x16x32_bf16 v[28:31], v[144:147], v[214:217], v[28:31]
	global_load_lds_dwordx4 v138, s[86:87]
	v_mfma_f32_16x16x32_bf16 v[20:23], v[152:155], v[214:217], v[20:23]
	v_mfma_f32_16x16x32_bf16 v[8:11], v[144:147], v[222:225], v[8:11]
	v_mfma_f32_16x16x32_bf16 v[4:7], v[152:155], v[222:225], v[4:7]
	s_setprio 0
	s_setprio 1
	v_mfma_f32_16x16x32_bf16 v[56:59], v[174:177], v[190:193], v[56:59]
	v_mfma_f32_16x16x32_bf16 v[48:51], v[182:185], v[190:193], v[48:51]
	v_mfma_f32_16x16x32_bf16 v[40:43], v[174:177], v[202:205], v[40:43]
	v_mfma_f32_16x16x32_bf16 v[32:35], v[182:185], v[202:205], v[32:35]
	v_mfma_f32_16x16x32_bf16 v[24:27], v[174:177], v[210:213], v[24:27]
	v_mfma_f32_16x16x32_bf16 v[16:19], v[182:185], v[210:213], v[16:19]
	v_mfma_f32_16x16x32_bf16 v[12:15], v[174:177], v[218:221], v[12:15]
	v_mfma_f32_16x16x32_bf16 v[0:3], v[182:185], v[218:221], v[0:3]
	v_mfma_f32_16x16x32_bf16 v[56:59], v[178:181], v[198:201], v[56:59]
	v_mfma_f32_16x16x32_bf16 v[48:51], v[186:189], v[198:201], v[48:51]
	v_mfma_f32_16x16x32_bf16 v[40:43], v[178:181], v[206:209], v[40:43]
	v_mfma_f32_16x16x32_bf16 v[32:35], v[186:189], v[206:209], v[32:35]
	v_mfma_f32_16x16x32_bf16 v[24:27], v[178:181], v[214:217], v[24:27]
	v_mfma_f32_16x16x32_bf16 v[16:19], v[186:189], v[214:217], v[16:19]
	v_mfma_f32_16x16x32_bf16 v[12:15], v[178:181], v[222:225], v[12:15]
	v_mfma_f32_16x16x32_bf16 v[0:3], v[186:189], v[222:225], v[0:3]
	s_setprio 0
	s_barrier
	s_add_i32 s62, 0, 0x18000
	s_add_i32 s63, 0, 0x1c000
	s_mov_b32 m0, s51
	v_add_u32_e32 v152, s62, v172
	v_add_u32_e32 v158, s63, v172
	v_add_u32_e32 v245, s62, v243
	v_add_u32_e32 v246, s63, v243
	global_load_lds_dwordx4 v132, s[42:43]
	s_mov_b32 m0, s60
	ds_read_b128 v[128:131], v152
	global_load_lds_dwordx4 v136, s[42:43]
	ds_read_b128 v[144:147], v245
	ds_read_b128 v[148:151], v152 offset:2048
	ds_read_b128 v[152:155], v245 offset:2048
	ds_read_b128 v[174:177], v158
	ds_read_b128 v[178:181], v246
	ds_read_b128 v[182:185], v158 offset:2048
	ds_read_b128 v[186:189], v246 offset:2048
	ds_read_b128 v[190:193], v173 offset:32768
	ds_read_b128 v[198:201], v244 offset:32768
	ds_read_b128 v[202:205], v173 offset:34816
	ds_read_b128 v[206:209], v244 offset:34816
	ds_read_b128 v[210:213], v173 offset:36864
	ds_read_b128 v[214:217], v244 offset:36864
	ds_read_b128 v[218:221], v173 offset:38912
	ds_read_b128 v[222:225], v244 offset:38912
	s_add_u32 s42, s42, 0x40000
	s_addc_u32 s43, s43, 0
	s_waitcnt vmcnt(6)
	s_waitcnt lgkmcnt(0)
	s_barrier
	s_setprio 1
	s_waitcnt lgkmcnt(0)
	v_mfma_f32_16x16x32_bf16 v[124:127], v[128:131], v[190:193], v[124:127]
	v_mfma_f32_16x16x32_bf16 v[116:119], v[148:151], v[190:193], v[116:119]
	v_mfma_f32_16x16x32_bf16 v[108:111], v[128:131], v[202:205], v[108:111]
	s_mov_b32 m0, s61
	v_mfma_f32_16x16x32_bf16 v[100:103], v[148:151], v[202:205], v[100:103]
	v_mfma_f32_16x16x32_bf16 v[92:95], v[128:131], v[210:213], v[92:95]
	global_load_lds_dwordx4 v132, s[42:43]
	v_mfma_f32_16x16x32_bf16 v[84:87], v[148:151], v[210:213], v[84:87]
	v_mfma_f32_16x16x32_bf16 v[76:79], v[128:131], v[218:221], v[76:79]
	v_mfma_f32_16x16x32_bf16 v[68:71], v[148:151], v[218:221], v[68:71]
	v_mfma_f32_16x16x32_bf16 v[124:127], v[144:147], v[198:201], v[124:127]
	v_mfma_f32_16x16x32_bf16 v[116:119], v[152:155], v[198:201], v[116:119]
	v_mfma_f32_16x16x32_bf16 v[108:111], v[144:147], v[206:209], v[108:111]
	s_mov_b32 m0, s64
	v_mfma_f32_16x16x32_bf16 v[100:103], v[152:155], v[206:209], v[100:103]
	v_mfma_f32_16x16x32_bf16 v[92:95], v[144:147], v[214:217], v[92:95]
	global_load_lds_dwordx4 v136, s[42:43]
	v_mfma_f32_16x16x32_bf16 v[84:87], v[152:155], v[214:217], v[84:87]
	v_mfma_f32_16x16x32_bf16 v[76:79], v[144:147], v[222:225], v[76:79]
	v_mfma_f32_16x16x32_bf16 v[68:71], v[152:155], v[222:225], v[68:71]
	s_setprio 0
	s_setprio 1
	v_mfma_f32_16x16x32_bf16 v[120:123], v[174:177], v[190:193], v[120:123]
	v_mfma_f32_16x16x32_bf16 v[112:115], v[182:185], v[190:193], v[112:115]
	v_mfma_f32_16x16x32_bf16 v[104:107], v[174:177], v[202:205], v[104:107]
	v_mfma_f32_16x16x32_bf16 v[96:99], v[182:185], v[202:205], v[96:99]
	v_mfma_f32_16x16x32_bf16 v[88:91], v[174:177], v[210:213], v[88:91]
	v_mfma_f32_16x16x32_bf16 v[80:83], v[182:185], v[210:213], v[80:83]
	v_mfma_f32_16x16x32_bf16 v[72:75], v[174:177], v[218:221], v[72:75]
	v_mfma_f32_16x16x32_bf16 v[64:67], v[182:185], v[218:221], v[64:67]
	v_mfma_f32_16x16x32_bf16 v[120:123], v[178:181], v[198:201], v[120:123]
	v_mfma_f32_16x16x32_bf16 v[112:115], v[186:189], v[198:201], v[112:115]
	v_mfma_f32_16x16x32_bf16 v[104:107], v[178:181], v[206:209], v[104:107]
	v_mfma_f32_16x16x32_bf16 v[96:99], v[186:189], v[206:209], v[96:99]
	v_mfma_f32_16x16x32_bf16 v[88:91], v[178:181], v[214:217], v[88:91]
	v_mfma_f32_16x16x32_bf16 v[80:83], v[186:189], v[214:217], v[80:83]
	v_mfma_f32_16x16x32_bf16 v[72:75], v[178:181], v[222:225], v[72:75]
	v_mfma_f32_16x16x32_bf16 v[64:67], v[186:189], v[222:225], v[64:67]
	s_setprio 0
	s_barrier
	s_add_i32 s42, s62, s48
	s_add_u32 s40, s40, 0x80
	s_addc_u32 s41, s41, 0
	s_mov_b32 m0, s42
	ds_read_b128 v[190:193], v173 offset:49152
	global_load_lds_dwordx4 v134, s[40:41]
	s_add_i32 m0, s42, 0x2000
	ds_read_b128 v[198:201], v244 offset:49152
	global_load_lds_dwordx4 v138, s[40:41]
	ds_read_b128 v[202:205], v173 offset:51200
	ds_read_b128 v[206:209], v244 offset:51200
	ds_read_b128 v[210:213], v173 offset:53248
	ds_read_b128 v[214:217], v244 offset:53248
	ds_read_b128 v[218:221], v173 offset:55296
	ds_read_b128 v[222:225], v244 offset:55296
	s_add_u32 s40, s40, 0x40000
	s_addc_u32 s41, s41, 0
	s_add_i32 s42, s63, s48
	s_waitcnt vmcnt(4)
	s_waitcnt lgkmcnt(0)
	s_barrier
	s_setprio 1
	s_waitcnt lgkmcnt(0)
	v_mfma_f32_16x16x32_bf16 v[60:63], v[128:131], v[190:193], v[60:63]
	v_mfma_f32_16x16x32_bf16 v[52:55], v[148:151], v[190:193], v[52:55]
	v_mfma_f32_16x16x32_bf16 v[44:47], v[128:131], v[202:205], v[44:47]
	s_mov_b32 m0, s42
	v_mfma_f32_16x16x32_bf16 v[36:39], v[148:151], v[202:205], v[36:39]
	v_mfma_f32_16x16x32_bf16 v[28:31], v[128:131], v[210:213], v[28:31]
	global_load_lds_dwordx4 v134, s[40:41]
	v_mfma_f32_16x16x32_bf16 v[20:23], v[148:151], v[210:213], v[20:23]
	v_mfma_f32_16x16x32_bf16 v[8:11], v[128:131], v[218:221], v[8:11]
	v_mfma_f32_16x16x32_bf16 v[4:7], v[148:151], v[218:221], v[4:7]
	v_mfma_f32_16x16x32_bf16 v[60:63], v[144:147], v[198:201], v[60:63]
	v_mfma_f32_16x16x32_bf16 v[52:55], v[152:155], v[198:201], v[52:55]
	v_mfma_f32_16x16x32_bf16 v[44:47], v[144:147], v[206:209], v[44:47]
	s_add_i32 m0, s42, 0x2000
	v_mfma_f32_16x16x32_bf16 v[36:39], v[152:155], v[206:209], v[36:39]
	v_mfma_f32_16x16x32_bf16 v[28:31], v[144:147], v[214:217], v[28:31]
	global_load_lds_dwordx4 v138, s[40:41]
	v_mfma_f32_16x16x32_bf16 v[20:23], v[152:155], v[214:217], v[20:23]
	v_mfma_f32_16x16x32_bf16 v[8:11], v[144:147], v[222:225], v[8:11]
	v_mfma_f32_16x16x32_bf16 v[4:7], v[152:155], v[222:225], v[4:7]
	s_setprio 0
	s_setprio 1
	v_mfma_f32_16x16x32_bf16 v[56:59], v[174:177], v[190:193], v[56:59]
	v_mfma_f32_16x16x32_bf16 v[48:51], v[182:185], v[190:193], v[48:51]
	v_mfma_f32_16x16x32_bf16 v[40:43], v[174:177], v[202:205], v[40:43]
	v_mfma_f32_16x16x32_bf16 v[32:35], v[182:185], v[202:205], v[32:35]
	v_mfma_f32_16x16x32_bf16 v[24:27], v[174:177], v[210:213], v[24:27]
	v_mfma_f32_16x16x32_bf16 v[16:19], v[182:185], v[210:213], v[16:19]
	v_mfma_f32_16x16x32_bf16 v[12:15], v[174:177], v[218:221], v[12:15]
	v_mfma_f32_16x16x32_bf16 v[0:3], v[182:185], v[218:221], v[0:3]
	v_mfma_f32_16x16x32_bf16 v[56:59], v[178:181], v[198:201], v[56:59]
	v_mfma_f32_16x16x32_bf16 v[48:51], v[186:189], v[198:201], v[48:51]
	v_mfma_f32_16x16x32_bf16 v[40:43], v[178:181], v[206:209], v[40:43]
	v_mfma_f32_16x16x32_bf16 v[32:35], v[186:189], v[206:209], v[32:35]
	v_mfma_f32_16x16x32_bf16 v[24:27], v[178:181], v[214:217], v[24:27]
	v_mfma_f32_16x16x32_bf16 v[16:19], v[186:189], v[214:217], v[16:19]
	v_mfma_f32_16x16x32_bf16 v[12:15], v[178:181], v[222:225], v[12:15]
	v_mfma_f32_16x16x32_bf16 v[0:3], v[186:189], v[222:225], v[0:3]
	s_setprio 0
	s_barrier
	s_add_i32 s85, s85, 2
	s_add_u32 s34, s34, 0x100
	s_addc_u32 s35, s35, 0
	s_add_u32 s83, s83, 0x100
	s_addc_u32 s84, s84, 0
	s_cmp_gt_u32 s85, 13
	s_cbranch_scc0 .LBB0_629
	s_and_b64 vcc, exec, s[2:3]
	s_cbranch_vccz .LBB0_632
	s_barrier

	.amdhsa_kernel _Z8yoco_fwd6Params
		.amdhsa_group_segment_fixed_size 0
		.amdhsa_private_segment_fixed_size 0
		.amdhsa_kernarg_size 456
		.amdhsa_user_sgpr_count 2
		.amdhsa_user_sgpr_dispatch_ptr 0
		.amdhsa_user_sgpr_queue_ptr 0
		.amdhsa_user_sgpr_kernarg_segment_ptr 1
		.amdhsa_user_sgpr_dispatch_id 0
		.amdhsa_user_sgpr_kernarg_preload_length 0
		.amdhsa_user_sgpr_kernarg_preload_offset 0
		.amdhsa_user_sgpr_private_segment_size 0
		.amdhsa_uses_dynamic_stack 0
		.amdhsa_enable_private_segment 0
		.amdhsa_system_sgpr_workgroup_id_x 1
		.amdhsa_system_sgpr_workgroup_id_y 0
		.amdhsa_system_sgpr_workgroup_id_z 0
		.amdhsa_system_sgpr_workgroup_info 0
		.amdhsa_system_vgpr_workitem_id 2
		.amdhsa_next_free_vgpr 248
		.amdhsa_next_free_sgpr 98
		.amdhsa_accum_offset 248
		.amdhsa_reserve_vcc 1
		.amdhsa_float_round_mode_32 0
		.amdhsa_float_round_mode_16_64 0
		.amdhsa_float_denorm_mode_32 3
		.amdhsa_float_denorm_mode_16_64 3
		.amdhsa_dx10_clamp 1
		.amdhsa_ieee_mode 1
		.amdhsa_fp16_overflow 0
		.amdhsa_tg_split 0
		.amdhsa_exception_fp_ieee_invalid_op 0
		.amdhsa_exception_fp_denorm_src 0
		.amdhsa_exception_fp_ieee_div_zero 0
		.amdhsa_exception_fp_ieee_overflow 0
		.amdhsa_exception_fp_ieee_underflow 0
		.amdhsa_exception_fp_ieee_inexact 0
		.amdhsa_exception_int_div_zero 0
	.end_amdhsa_kernel

amdhsa.kernels:
  - .agpr_count:     0
    .args:
      - .offset:         0
        .size:           200
        .value_kind:     by_value
      - .offset:         200
        .size:           4
        .value_kind:     hidden_block_count_x
      - .offset:         204
        .size:           4
        .value_kind:     hidden_block_count_y
      - .offset:         208
        .size:           4
        .value_kind:     hidden_block_count_z
      - .offset:         212
        .size:           2
        .value_kind:     hidden_group_size_x
      - .offset:         214
        .size:           2
        .value_kind:     hidden_group_size_y
      - .offset:         216
        .size:           2
        .value_kind:     hidden_group_size_z
      - .offset:         218
        .size:           2
        .value_kind:     hidden_remainder_x
      - .offset:         220
        .size:           2
        .value_kind:     hidden_remainder_y
      - .offset:         222
        .size:           2
        .value_kind:     hidden_remainder_z
      - .offset:         240
        .size:           8
        .value_kind:     hidden_global_offset_x
      - .offset:         248
        .size:           8
        .value_kind:     hidden_global_offset_y
      - .offset:         256
        .size:           8
        .value_kind:     hidden_global_offset_z
      - .offset:         264
        .size:           2
        .value_kind:     hidden_grid_dims
      - .offset:         288
        .size:           8
        .value_kind:     hidden_multigrid_sync_arg
      - .offset:         320
        .size:           4
        .value_kind:     hidden_dynamic_lds_size
    .group_segment_fixed_size: 0
    .kernarg_segment_align: 8
    .kernarg_segment_size: 456
    .language:       OpenCL C
    .language_version:
      - 2
      - 0
    .max_flat_workgroup_size: 512
    .name:           _Z8yoco_fwd6Params
    .private_segment_fixed_size: 0
    .sgpr_count:     104
    .sgpr_spill_count: 130
    .symbol:         _Z8yoco_fwd6Params.kd
    .uniform_work_group_size: 1
    .uses_dynamic_stack: false
    .vgpr_count:     248
    .vgpr_spill_count: 0
    .wavefront_size: 64
